# v112 + UP loop 16-read load phases at equal priority from their start
# baseline (speedup 1.0000x reference)
.LBB0_1328:
	s_add_u32 s44, s42, 0xfffc0080
	s_addc_u32 s45, s43, -1
	s_add_i32 s53, 0, 0x10000
	s_cmp_eq_u32 s52, 12
	s_cselect_b32 s47, s1, s45
	s_cselect_b32 s46, s41, s44
	s_cselect_b32 s45, s48, s51
	s_cselect_b32 s44, s49, s50
	s_add_i32 s56, 0, 0x14000
	v_add_u32_e32 v94, s53, v186
	v_add_u32_e32 v174, s56, v186
	ds_read_b128 v[82:85], v94
	ds_read_b128 v[86:89], v94 offset:1024
	ds_read_b128 v[90:93], v94 offset:2048
	ds_read_b128 v[94:97], v94 offset:3072
	ds_read_b128 v[162:165], v174
	ds_read_b128 v[166:169], v174 offset:1024
	ds_read_b128 v[170:173], v174 offset:2048
	ds_read_b128 v[174:177], v174 offset:3072
	s_add_u32 s100, s42, 0xfffc0000
	s_addc_u32 s101, s43, -1
	v_lshl_add_u64 v[198:199], s[100:101], 0, v[148:149]
	s_mov_b32 m0, s33
	s_nop 0
	global_load_lds_dwordx4 v[198:199], off
	v_lshl_add_u64 v[198:199], s[100:101], 0, v[150:151]
	s_mov_b32 m0, s14
	s_nop 0
	global_load_lds_dwordx4 v[198:199], off
	v_lshl_add_u64 v[198:199], s[42:43], 0, v[158:159]
	s_add_i32 m0, s2, 0xc000
	ds_read_b128 v[178:181], v187
	ds_read_b128 v[182:185], v187 offset:1024
	ds_read_b128 v[190:193], v187 offset:2048
	ds_read_b128 v[194:197], v187 offset:3072
	ds_read_b128 v[204:207], v187 offset:4096
	ds_read_b128 v[208:211], v187 offset:5120
	ds_read_b128 v[214:217], v187 offset:6144
	ds_read_b128 v[218:221], v187 offset:7168
	global_load_lds_dwordx4 v[198:199], off
	v_lshl_add_u64 v[198:199], s[42:43], 0, v[160:161]
	s_add_i32 m0, s2, 0xe000
	s_nop 0
	global_load_lds_dwordx4 v[198:199], off
	s_waitcnt vmcnt(8)
	s_waitcnt lgkmcnt(0)
	s_barrier
	v_mfma_f32_16x16x32_bf16 v[144:147], v[82:85], v[178:181], v[144:147]
	v_mfma_f32_16x16x32_bf16 v[140:143], v[90:93], v[178:181], v[140:143]
	v_mfma_f32_16x16x32_bf16 v[128:131], v[82:85], v[190:193], v[128:131]
	v_mfma_f32_16x16x32_bf16 v[124:127], v[90:93], v[190:193], v[124:127]
	v_mfma_f32_16x16x32_bf16 v[112:115], v[82:85], v[204:207], v[112:115]
	v_mfma_f32_16x16x32_bf16 v[108:111], v[90:93], v[204:207], v[108:111]
	v_mfma_f32_16x16x32_bf16 v[78:81], v[82:85], v[214:217], v[78:81]
	v_mfma_f32_16x16x32_bf16 v[74:77], v[90:93], v[214:217], v[74:77]
	v_mfma_f32_16x16x32_bf16 v[144:147], v[86:89], v[182:185], v[144:147]
	v_mfma_f32_16x16x32_bf16 v[140:143], v[94:97], v[182:185], v[140:143]
	v_mfma_f32_16x16x32_bf16 v[128:131], v[86:89], v[194:197], v[128:131]
	v_mfma_f32_16x16x32_bf16 v[124:127], v[94:97], v[194:197], v[124:127]
	v_mfma_f32_16x16x32_bf16 v[112:115], v[86:89], v[208:211], v[112:115]
	v_mfma_f32_16x16x32_bf16 v[108:111], v[94:97], v[208:211], v[108:111]
	v_mfma_f32_16x16x32_bf16 v[78:81], v[86:89], v[218:221], v[78:81]
	v_mfma_f32_16x16x32_bf16 v[74:77], v[94:97], v[218:221], v[74:77]
	s_setprio 0
	s_setprio 1
	v_mfma_f32_16x16x32_bf16 v[136:139], v[162:165], v[178:181], v[136:139]
	v_mfma_f32_16x16x32_bf16 v[132:135], v[170:173], v[178:181], v[132:135]
	v_mfma_f32_16x16x32_bf16 v[120:123], v[162:165], v[190:193], v[120:123]
	v_mfma_f32_16x16x32_bf16 v[116:119], v[170:173], v[190:193], v[116:119]
	v_mfma_f32_16x16x32_bf16 v[104:107], v[162:165], v[204:207], v[104:107]
	v_mfma_f32_16x16x32_bf16 v[100:103], v[170:173], v[204:207], v[100:103]
	v_mfma_f32_16x16x32_bf16 v[70:73], v[162:165], v[214:217], v[70:73]
	v_mfma_f32_16x16x32_bf16 v[66:69], v[170:173], v[214:217], v[66:69]
	v_mfma_f32_16x16x32_bf16 v[136:139], v[166:169], v[182:185], v[136:139]
	v_mfma_f32_16x16x32_bf16 v[132:135], v[174:177], v[182:185], v[132:135]
	v_mfma_f32_16x16x32_bf16 v[120:123], v[166:169], v[194:197], v[120:123]
	v_mfma_f32_16x16x32_bf16 v[116:119], v[174:177], v[194:197], v[116:119]
	v_mfma_f32_16x16x32_bf16 v[104:107], v[166:169], v[208:211], v[104:107]
	v_mfma_f32_16x16x32_bf16 v[100:103], v[174:177], v[208:211], v[100:103]
	v_mfma_f32_16x16x32_bf16 v[70:73], v[166:169], v[218:221], v[70:73]
	v_mfma_f32_16x16x32_bf16 v[66:69], v[174:177], v[218:221], v[66:69]
	s_setprio 0
	s_barrier
	s_add_i32 s53, s53, s9
	v_lshl_add_u64 v[198:199], s[44:45], 0, v[98:99]
	s_mov_b32 m0, s53
	ds_read_b128 v[178:181], v187 offset:16384
	ds_read_b128 v[182:185], v187 offset:17408
	ds_read_b128 v[190:193], v187 offset:18432
	ds_read_b128 v[194:197], v187 offset:19456
	ds_read_b128 v[204:207], v187 offset:20480
	ds_read_b128 v[208:211], v187 offset:21504
	ds_read_b128 v[214:217], v187 offset:22528
	ds_read_b128 v[218:221], v187 offset:23552
	s_setprio 1
	global_load_lds_dwordx4 v[198:199], off
	s_add_i32 m0, s53, 0x2000
	s_add_u32 s54, s44, 0x40000
	v_lshl_add_u64 v[222:223], s[44:45], 0, v[152:153]
	s_addc_u32 s55, s45, 0
	s_add_i32 s53, s56, s9
	global_load_lds_dwordx4 v[222:223], off
	v_lshl_add_u64 v[224:225], s[54:55], 0, v[98:99]
	s_mov_b32 m0, s53
	s_nop 0
	global_load_lds_dwordx4 v[224:225], off
	v_lshl_add_u64 v[224:225], s[54:55], 0, v[152:153]
	s_add_i32 m0, s53, 0x2000
	s_nop 0
	global_load_lds_dwordx4 v[224:225], off
	s_waitcnt vmcnt(6)
	s_waitcnt lgkmcnt(0)
	s_barrier
	v_mfma_f32_16x16x32_bf16 v[62:65], v[82:85], v[178:181], v[62:65]
	v_mfma_f32_16x16x32_bf16 v[58:61], v[90:93], v[178:181], v[58:61]
	v_mfma_f32_16x16x32_bf16 v[46:49], v[82:85], v[190:193], v[46:49]
	v_mfma_f32_16x16x32_bf16 v[42:45], v[90:93], v[190:193], v[42:45]
	v_mfma_f32_16x16x32_bf16 v[30:33], v[82:85], v[204:207], v[30:33]
	v_mfma_f32_16x16x32_bf16 v[26:29], v[90:93], v[204:207], v[26:29]
	v_mfma_f32_16x16x32_bf16 v[14:17], v[82:85], v[214:217], v[14:17]
	v_mfma_f32_16x16x32_bf16 v[10:13], v[90:93], v[214:217], v[10:13]
	v_mfma_f32_16x16x32_bf16 v[62:65], v[86:89], v[182:185], v[62:65]
	v_mfma_f32_16x16x32_bf16 v[58:61], v[94:97], v[182:185], v[58:61]
	v_mfma_f32_16x16x32_bf16 v[46:49], v[86:89], v[194:197], v[46:49]
	v_mfma_f32_16x16x32_bf16 v[42:45], v[94:97], v[194:197], v[42:45]
	v_mfma_f32_16x16x32_bf16 v[30:33], v[86:89], v[208:211], v[30:33]
	v_mfma_f32_16x16x32_bf16 v[26:29], v[94:97], v[208:211], v[26:29]
	v_mfma_f32_16x16x32_bf16 v[14:17], v[86:89], v[218:221], v[14:17]
	v_mfma_f32_16x16x32_bf16 v[10:13], v[94:97], v[218:221], v[10:13]
	s_setprio 0
	s_setprio 1
	v_mfma_f32_16x16x32_bf16 v[54:57], v[162:165], v[178:181], v[54:57]
	v_mfma_f32_16x16x32_bf16 v[50:53], v[170:173], v[178:181], v[50:53]
	v_mfma_f32_16x16x32_bf16 v[38:41], v[162:165], v[190:193], v[38:41]
	v_mfma_f32_16x16x32_bf16 v[34:37], v[170:173], v[190:193], v[34:37]
	v_mfma_f32_16x16x32_bf16 v[22:25], v[162:165], v[204:207], v[22:25]
	v_mfma_f32_16x16x32_bf16 v[18:21], v[170:173], v[204:207], v[18:21]
	v_mfma_f32_16x16x32_bf16 v[6:9], v[162:165], v[214:217], v[6:9]
	v_mfma_f32_16x16x32_bf16 v[2:5], v[170:173], v[214:217], v[2:5]
	v_mfma_f32_16x16x32_bf16 v[54:57], v[166:169], v[182:185], v[54:57]
	v_mfma_f32_16x16x32_bf16 v[50:53], v[174:177], v[182:185], v[50:53]
	v_mfma_f32_16x16x32_bf16 v[38:41], v[166:169], v[194:197], v[38:41]
	v_mfma_f32_16x16x32_bf16 v[34:37], v[174:177], v[194:197], v[34:37]
	v_mfma_f32_16x16x32_bf16 v[22:25], v[166:169], v[208:211], v[22:25]
	v_mfma_f32_16x16x32_bf16 v[18:21], v[174:177], v[208:211], v[18:21]
	v_mfma_f32_16x16x32_bf16 v[6:9], v[166:169], v[218:221], v[6:9]
	v_mfma_f32_16x16x32_bf16 v[2:5], v[174:177], v[218:221], v[2:5]
	s_barrier
	s_add_i32 s53, 0, 0x18000
	s_add_i32 s54, 0, 0x1c000
	v_add_u32_e32 v94, s53, v186
	v_add_u32_e32 v174, s54, v186
	ds_read_b128 v[82:85], v94
	ds_read_b128 v[86:89], v94 offset:1024
	ds_read_b128 v[90:93], v94 offset:2048
	ds_read_b128 v[94:97], v94 offset:3072
	ds_read_b128 v[162:165], v174
	ds_read_b128 v[166:169], v174 offset:1024
	ds_read_b128 v[170:173], v174 offset:2048
	ds_read_b128 v[174:177], v174 offset:3072
	v_lshl_add_u64 v[224:225], s[46:47], 0, v[148:149]
	s_mov_b32 m0, s2
	v_lshl_add_u64 v[226:227], s[46:47], 0, v[150:151]
	global_load_lds_dwordx4 v[224:225], off
	s_mov_b32 m0, s4
	s_nop 0
	global_load_lds_dwordx4 v[226:227], off
	s_add_u32 s46, s46, 0x40000
	s_addc_u32 s47, s47, 0
	s_mov_b32 m0, s12
	v_lshl_add_u64 v[228:229], s[46:47], 0, v[148:149]
	ds_read_b128 v[178:181], v187 offset:32768
	ds_read_b128 v[182:185], v187 offset:33792
	ds_read_b128 v[190:193], v187 offset:34816
	ds_read_b128 v[194:197], v187 offset:35840
	ds_read_b128 v[204:207], v187 offset:36864
	ds_read_b128 v[208:211], v187 offset:37888
	ds_read_b128 v[214:217], v187 offset:38912
	ds_read_b128 v[218:221], v187 offset:39936
	global_load_lds_dwordx4 v[228:229], off
	v_lshl_add_u64 v[228:229], s[46:47], 0, v[150:151]
	s_mov_b32 m0, s13
	s_nop 0
	global_load_lds_dwordx4 v[228:229], off
	s_waitcnt vmcnt(8)
	s_waitcnt lgkmcnt(0)
	s_barrier
	v_mfma_f32_16x16x32_bf16 v[144:147], v[82:85], v[178:181], v[144:147]
	v_mfma_f32_16x16x32_bf16 v[140:143], v[90:93], v[178:181], v[140:143]
	v_mfma_f32_16x16x32_bf16 v[128:131], v[82:85], v[190:193], v[128:131]
	v_mfma_f32_16x16x32_bf16 v[124:127], v[90:93], v[190:193], v[124:127]
	v_mfma_f32_16x16x32_bf16 v[112:115], v[82:85], v[204:207], v[112:115]
	v_mfma_f32_16x16x32_bf16 v[108:111], v[90:93], v[204:207], v[108:111]
	v_mfma_f32_16x16x32_bf16 v[78:81], v[82:85], v[214:217], v[78:81]
	v_mfma_f32_16x16x32_bf16 v[74:77], v[90:93], v[214:217], v[74:77]
	v_mfma_f32_16x16x32_bf16 v[144:147], v[86:89], v[182:185], v[144:147]
	v_mfma_f32_16x16x32_bf16 v[140:143], v[94:97], v[182:185], v[140:143]
	v_mfma_f32_16x16x32_bf16 v[128:131], v[86:89], v[194:197], v[128:131]
	v_mfma_f32_16x16x32_bf16 v[124:127], v[94:97], v[194:197], v[124:127]
	v_mfma_f32_16x16x32_bf16 v[112:115], v[86:89], v[208:211], v[112:115]
	v_mfma_f32_16x16x32_bf16 v[108:111], v[94:97], v[208:211], v[108:111]
	v_mfma_f32_16x16x32_bf16 v[78:81], v[86:89], v[218:221], v[78:81]
	v_mfma_f32_16x16x32_bf16 v[74:77], v[94:97], v[218:221], v[74:77]
	s_setprio 0
	s_setprio 1
	v_mfma_f32_16x16x32_bf16 v[136:139], v[162:165], v[178:181], v[136:139]
	v_mfma_f32_16x16x32_bf16 v[132:135], v[170:173], v[178:181], v[132:135]
	v_mfma_f32_16x16x32_bf16 v[120:123], v[162:165], v[190:193], v[120:123]
	v_mfma_f32_16x16x32_bf16 v[116:119], v[170:173], v[190:193], v[116:119]
	v_mfma_f32_16x16x32_bf16 v[104:107], v[162:165], v[204:207], v[104:107]
	v_mfma_f32_16x16x32_bf16 v[100:103], v[170:173], v[204:207], v[100:103]
	v_mfma_f32_16x16x32_bf16 v[70:73], v[162:165], v[214:217], v[70:73]
	v_mfma_f32_16x16x32_bf16 v[66:69], v[170:173], v[214:217], v[66:69]
	v_mfma_f32_16x16x32_bf16 v[136:139], v[166:169], v[182:185], v[136:139]
	v_mfma_f32_16x16x32_bf16 v[132:135], v[174:177], v[182:185], v[132:135]
	v_mfma_f32_16x16x32_bf16 v[120:123], v[166:169], v[194:197], v[120:123]
	v_mfma_f32_16x16x32_bf16 v[116:119], v[174:177], v[194:197], v[116:119]
	v_mfma_f32_16x16x32_bf16 v[104:107], v[166:169], v[208:211], v[104:107]
	v_mfma_f32_16x16x32_bf16 v[100:103], v[174:177], v[208:211], v[100:103]
	v_mfma_f32_16x16x32_bf16 v[70:73], v[166:169], v[218:221], v[70:73]
	v_mfma_f32_16x16x32_bf16 v[66:69], v[174:177], v[218:221], v[66:69]
	s_setprio 0
	s_barrier
	s_add_i32 s46, s53, s9
	v_lshl_add_u64 v[198:199], v[198:199], 0, s[28:29]
	s_mov_b32 m0, s46
	ds_read_b128 v[178:181], v187 offset:49152
	ds_read_b128 v[182:185], v187 offset:50176
	ds_read_b128 v[190:193], v187 offset:51200
	ds_read_b128 v[194:197], v187 offset:52224
	ds_read_b128 v[204:207], v187 offset:53248
	ds_read_b128 v[208:211], v187 offset:54272
	ds_read_b128 v[214:217], v187 offset:55296
	ds_read_b128 v[218:221], v187 offset:56320
	s_setprio 1
	global_load_lds_dwordx4 v[198:199], off
	s_add_i32 m0, s46, 0x2000
	s_add_u32 s44, s44, 0x40080
	v_lshl_add_u64 v[198:199], v[222:223], 0, s[28:29]
	s_addc_u32 s45, s45, 0
	s_add_i32 s46, s54, s9
	global_load_lds_dwordx4 v[198:199], off
	v_lshl_add_u64 v[198:199], s[44:45], 0, v[98:99]
	s_mov_b32 m0, s46
	s_nop 0
	global_load_lds_dwordx4 v[198:199], off
	v_lshl_add_u64 v[198:199], s[44:45], 0, v[152:153]
	s_add_i32 m0, s46, 0x2000
	s_nop 0
	global_load_lds_dwordx4 v[198:199], off
	s_waitcnt vmcnt(6)
	s_waitcnt lgkmcnt(0)
	s_barrier
	v_mfma_f32_16x16x32_bf16 v[62:65], v[82:85], v[178:181], v[62:65]
	v_mfma_f32_16x16x32_bf16 v[58:61], v[90:93], v[178:181], v[58:61]
	v_mfma_f32_16x16x32_bf16 v[46:49], v[82:85], v[190:193], v[46:49]
	v_mfma_f32_16x16x32_bf16 v[42:45], v[90:93], v[190:193], v[42:45]
	v_mfma_f32_16x16x32_bf16 v[30:33], v[82:85], v[204:207], v[30:33]
	v_mfma_f32_16x16x32_bf16 v[26:29], v[90:93], v[204:207], v[26:29]
	v_mfma_f32_16x16x32_bf16 v[14:17], v[82:85], v[214:217], v[14:17]
	v_mfma_f32_16x16x32_bf16 v[10:13], v[90:93], v[214:217], v[10:13]
	v_mfma_f32_16x16x32_bf16 v[62:65], v[86:89], v[182:185], v[62:65]
	v_mfma_f32_16x16x32_bf16 v[58:61], v[94:97], v[182:185], v[58:61]
	v_mfma_f32_16x16x32_bf16 v[46:49], v[86:89], v[194:197], v[46:49]
	v_mfma_f32_16x16x32_bf16 v[42:45], v[94:97], v[194:197], v[42:45]
	v_mfma_f32_16x16x32_bf16 v[30:33], v[86:89], v[208:211], v[30:33]
	v_mfma_f32_16x16x32_bf16 v[26:29], v[94:97], v[208:211], v[26:29]
	v_mfma_f32_16x16x32_bf16 v[14:17], v[86:89], v[218:221], v[14:17]
	v_mfma_f32_16x16x32_bf16 v[10:13], v[94:97], v[218:221], v[10:13]
	s_setprio 0
	s_setprio 1
	v_mfma_f32_16x16x32_bf16 v[54:57], v[162:165], v[178:181], v[54:57]
	v_mfma_f32_16x16x32_bf16 v[50:53], v[170:173], v[178:181], v[50:53]
	v_mfma_f32_16x16x32_bf16 v[38:41], v[162:165], v[190:193], v[38:41]
	v_mfma_f32_16x16x32_bf16 v[34:37], v[170:173], v[190:193], v[34:37]
	v_mfma_f32_16x16x32_bf16 v[22:25], v[162:165], v[204:207], v[22:25]
	v_mfma_f32_16x16x32_bf16 v[18:21], v[170:173], v[204:207], v[18:21]
	v_mfma_f32_16x16x32_bf16 v[6:9], v[162:165], v[214:217], v[6:9]
	v_mfma_f32_16x16x32_bf16 v[2:5], v[170:173], v[214:217], v[2:5]
	v_mfma_f32_16x16x32_bf16 v[54:57], v[166:169], v[182:185], v[54:57]
	v_mfma_f32_16x16x32_bf16 v[50:53], v[174:177], v[182:185], v[50:53]
	v_mfma_f32_16x16x32_bf16 v[38:41], v[166:169], v[194:197], v[38:41]
	v_mfma_f32_16x16x32_bf16 v[34:37], v[174:177], v[194:197], v[34:37]
	v_mfma_f32_16x16x32_bf16 v[22:25], v[166:169], v[208:211], v[22:25]
	v_mfma_f32_16x16x32_bf16 v[18:21], v[174:177], v[208:211], v[18:21]
	v_mfma_f32_16x16x32_bf16 v[6:9], v[166:169], v[218:221], v[6:9]
	v_mfma_f32_16x16x32_bf16 v[2:5], v[174:177], v[218:221], v[2:5]
	s_barrier
	s_add_i32 s52, s52, 2
	s_add_u32 s42, s42, 0x100
	s_addc_u32 s43, s43, 0
	s_add_u32 s50, s50, 0x100
	s_addc_u32 s51, s51, 0
	s_cmp_gt_u32 s52, 13
	s_cbranch_scc0 .LBB0_1328
	s_and_b64 vcc, exec, s[76:77]
	s_cbranch_vccz .LBB0_1331
	s_barrier
